# GEMM tile decode: the group-size division (always 4 for these shapes) replaced by shift and mask in four GEMM unit loops
# speedup vs baseline: 1.0071x; 1.0071x over previous
;     __device__ bool next(int i, pg8::Unit& u) const { const int j = i / 3, n = i - 3 * j; pg8::Unit t; if (!S4.next(j, t)) return false; u.pm = t.pm; u.pn = n * 4 + t.pn; return true; }
;     __host__ __device__ bool next(int i, Unit& u) const {
;         const long L = (long)i * G + c; if (L >= nwg) return false;
;         int wgid = (int)L; { const int q = nwg / NXCD, r = nwg % NXCD, xcd = wgid % NXCD, off = wgid / NXCD; wgid = (xcd < r ? xcd * (q + 1) : r * (q + 1) + (xcd - r) * q) + off; }
;         const int nig = WGM * nN, gid = wgid / nig, fm = gid * WGM, gsz = (nM - fm) < WGM ? (nM - fm) : WGM;
;         u.pm = fm + ((wgid % nig) % gsz); u.pn = (wgid % nig) / gsz; return true;
;     }
.LBB0_252:
	s_add_i32 s30, s30, 1
	s_mul_i32 s0, s30, s75
	s_mul_hi_u32 s1, s30, s74
	s_add_i32 s1, s1, s0
	s_mul_i32 s0, s30, s74
	v_readlane_b32 s7, v252, 44
	s_add_u32 s10, s0, s7
	v_readlane_b32 s0, v251, 19
	s_addc_u32 s11, s1, s0
	v_mov_b64_e32 v[2:3], 0xb00
	v_cmp_lt_i64_e64 s[0:1], s[10:11], v[2:3]
	v_mov_b64_e32 v[2:3], 0xaff
	v_cmp_gt_i64_e32 vcc, s[10:11], v[2:3]
	s_cbranch_vccnz .LBB0_254
	s_ashr_i32 s6, s10, 31
	s_lshr_b32 s6, s6, 29
	s_add_i32 s6, s10, s6
	s_ashr_i32 s7, s6, 3
	s_and_b32 s6, s6, -8
	s_sub_i32 s6, s10, s6
	s_cmp_lt_i32 s6, 0
	s_movk_i32 s8, 0x161
	s_cselect_b32 s8, s8, 0x160
	s_mul_i32 s6, s8, s6
	s_add_i32 s6, s6, s7
	s_mul_hi_i32 s7, s6, 0x2e8ba2e9
	s_lshr_b32 s8, s7, 31
	s_ashr_i32 s7, s7, 4
	s_add_i32 s7, s7, s8
	s_lshl_b32 s8, s7, 2
	s_mulk_i32 s7, 0x58
	s_sub_i32 s7, s6, s7
	s_lshr_b32 s6, s7, 2
	s_and_b32 s7, s7, 3
	s_add_i32 s8, s7, s8

;     __device__ bool next(int i, pg8::Unit& u) const { const int j = i / 3, n = i - 3 * j; pg8::Unit t; if (!S4.next(j, t)) return false; u.pm = t.pm; u.pn = n * 4 + t.pn; return true; }
;     __host__ __device__ bool next(int i, Unit& u) const {
;         const long L = (long)i * G + c; if (L >= nwg) return false;
;         int wgid = (int)L; { const int q = nwg / NXCD, r = nwg % NXCD, xcd = wgid % NXCD, off = wgid / NXCD; wgid = (xcd < r ? xcd * (q + 1) : r * (q + 1) + (xcd - r) * q) + off; }
;         const int nig = WGM * nN, gid = wgid / nig, fm = gid * WGM, gsz = (nM - fm) < WGM ? (nM - fm) : WGM;
;         u.pm = fm + ((wgid % nig) % gsz); u.pn = (wgid % nig) / gsz; return true;
;     }
.LBB0_735:
	s_ashr_i32 s6, s8, 3
	s_add_i32 s6, s10, s6
	s_ashr_i32 s7, s6, 31
	s_lshr_b32 s7, s7, 26
	s_add_i32 s7, s6, s7
	s_ashr_i32 s8, s7, 6
	s_lshl_b32 s8, s8, 2
	s_andn2_b32 s7, s7, 63
	s_sub_i32 s7, s6, s7
	s_lshr_b32 s6, s7, 2
	s_and_b32 s7, s7, 3
	s_add_i32 s8, s7, s8

;     __device__ bool next(int i, pg8::Unit& u) const { const int j = i / 3, n = i - 3 * j; pg8::Unit t; if (!S4.next(j, t)) return false; u.pm = t.pm; u.pn = n * 4 + t.pn; return true; }
;     __host__ __device__ bool next(int i, Unit& u) const {
;         const long L = (long)i * G + c; if (L >= nwg) return false;
;         int wgid = (int)L; { const int q = nwg / NXCD, r = nwg % NXCD, xcd = wgid % NXCD, off = wgid / NXCD; wgid = (xcd < r ? xcd * (q + 1) : r * (q + 1) + (xcd - r) * q) + off; }
;         const int nig = WGM * nN, gid = wgid / nig, fm = gid * WGM, gsz = (nM - fm) < WGM ? (nM - fm) : WGM;
;         u.pm = fm + ((wgid % nig) % gsz); u.pn = (wgid % nig) / gsz; return true;
;     }
.LBB0_1243:
	s_add_i32 s27, s27, 1
	s_mul_i32 s0, s27, s75
	s_mul_hi_u32 s1, s27, s74
	s_add_i32 s1, s1, s0
	s_mul_i32 s0, s27, s74
	v_readlane_b32 s7, v252, 44
	s_add_u32 s10, s0, s7
	v_readlane_b32 s0, v251, 19
	s_addc_u32 s11, s1, s0
	v_mov_b64_e32 v[2:3], 0x600
	v_cmp_lt_i64_e64 s[0:1], s[10:11], v[2:3]
	v_mov_b64_e32 v[2:3], 0x5ff
	v_cmp_gt_i64_e32 vcc, s[10:11], v[2:3]
	s_cbranch_vccnz .LBB0_1245
	s_ashr_i32 s6, s10, 31
	s_lshr_b32 s6, s6, 29
	s_add_i32 s6, s10, s6
	s_ashr_i32 s7, s6, 3
	s_and_b32 s6, s6, -8
	s_sub_i32 s6, s10, s6
	s_cmp_lt_i32 s6, 0
	s_movk_i32 s8, 0xc1
	s_cselect_b32 s8, s8, 0xc0
	s_mul_i32 s6, s8, s6
	s_add_i32 s6, s6, s7
	s_mul_hi_i32 s7, s6, 0x2aaaaaab
	s_lshr_b32 s8, s7, 31
	s_ashr_i32 s7, s7, 3
	s_add_i32 s7, s7, s8
	s_lshl_b32 s8, s7, 2
	s_mul_i32 s7, s7, 48
	s_sub_i32 s7, s6, s7
	s_lshr_b32 s6, s7, 2
	s_and_b32 s7, s7, 3
	s_add_i32 s8, s7, s8

;     __device__ bool next(int i, pg8::Unit& u) const { const int j = i / 3, n = i - 3 * j; pg8::Unit t; if (!S4.next(j, t)) return false; u.pm = t.pm; u.pn = n * 4 + t.pn; return true; }
;     __host__ __device__ bool next(int i, Unit& u) const {
;         const long L = (long)i * G + c; if (L >= nwg) return false;
;         int wgid = (int)L; { const int q = nwg / NXCD, r = nwg % NXCD, xcd = wgid % NXCD, off = wgid / NXCD; wgid = (xcd < r ? xcd * (q + 1) : r * (q + 1) + (xcd - r) * q) + off; }
;         const int nig = WGM * nN, gid = wgid / nig, fm = gid * WGM, gsz = (nM - fm) < WGM ? (nM - fm) : WGM;
;         u.pm = fm + ((wgid % nig) % gsz); u.pn = (wgid % nig) / gsz; return true;
;     }
.LBB0_1456:
	s_ashr_i32 s6, s8, 3
	s_add_i32 s6, s10, s6
	s_ashr_i32 s7, s6, 31
	s_lshr_b32 s7, s7, 28
	s_add_i32 s7, s6, s7
	s_ashr_i32 s8, s7, 4
	s_lshl_b32 s8, s8, 2
	s_and_b32 s7, s7, -16
	s_sub_i32 s7, s6, s7
	s_lshr_b32 s6, s7, 2
	s_and_b32 s7, s7, 3
	s_add_i32 s8, s7, s8
